# guarded L1-only barrier acquires, with the placement bit masked off in the second grid barrier's generation compares (the fallback path was verified by forcing it)
# speedup vs baseline: 1.0043x; 1.0043x over previous
.LBB0_514:
	global_load_dword v2, v[4:5], off sc1
	global_load_dword v6, v[4:5], off offset:256 sc1
	global_load_dword v7, v[4:5], off offset:512 sc1
	global_load_dword v8, v[4:5], off offset:768 sc1
	s_mov_b64 s[8:9], -1
	s_waitcnt vmcnt(0)
	v_min_u32_e32 v2, v2, v6
	v_min3_u32 v2, v2, v7, v8
	v_and_b32_e32 v2, 0xff, v2
	v_cmp_gt_u32_e64 s[12:13], 2, v2
	v_cndmask_b32_e64 v2, 0, 1, s[12:13]
	v_cmp_ne_u32_e32 vcc, 0, v2
	s_mov_b64 s[10:11], -1
	s_cbranch_vccz .LBB0_513
	s_and_b32 s1, s0, 0xff
	s_cmp_eq_u32 s1, 0
	s_mov_b64 s[12:13], -1
	s_sleep 1
	s_cbranch_scc0 .LBB0_524
	global_load_dword v2, v3, s[34:35] sc1
	s_waitcnt vmcnt(0)
	v_cmp_eq_u32_e32 vcc, 0, v2
	s_cbranch_vccnz .LBB0_526
	s_mov_b64 s[12:13], 0

.LBB0_532:
	v_mov_b32_e32 v2, 0
	global_load_dword v3, v2, s[6:7] sc1
	s_mov_b32 s0, 1
	s_waitcnt vmcnt(0)
	v_and_b32_e32 v9, 0xff, v3
	v_cmp_lt_u32_e32 vcc, 1, v9
	s_cbranch_vccz .Lpp_534
	s_branch .LBB0_542

.LBB0_536:
	global_load_dword v3, v2, s[6:7] sc1
	s_add_i32 s0, s0, 1
	s_mov_b64 s[8:9], -1
	s_waitcnt vmcnt(1)
	v_and_b32_e32 v9, 0xff, v3
	v_cmp_lt_u32_e64 s[4:5], 1, v9
	s_branch .LBB0_533
